# attention phase: every other group of 16 CUs runs its pool_up GEMM tiles before its attention units (second trip through the phase body), so the two halves' pool_up bursts overlap the other half's att
# baseline (speedup 1.0000x reference)
; #define LAS __attribute__((address_space(3)))
; __device__ __forceinline__ int opaque_tid(int wv) { int t = wv * 64 + (int)__builtin_amdgcn_mbcnt_hi(~0u, __builtin_amdgcn_mbcnt_lo(~0u, 0u)); asm volatile("" : "+v"(t)); return t; }
; __device__ __forceinline__ void phase_attn(const Args& a, int l, LAS unsigned char* lds, int vcu, int G, int wv) {
;     ...
;     const int sp0 = (G == 256) ? ((vcu >= 33 && vcu < 64) ? vcu - 33 : (vcu == 65 ? 31 : -1)) : (vcu < 32 ? vcu : -1);
;     const int nmain = (vcu < 512) ? 2 * ((512 - vcu + G - 1) / G) : 0, nspec = (G == 256) ? (sp0 >= 0 ? 1 : 0) : ((vcu < 32) ? (32 - vcu + G - 1) / G : 0);
; __global__ void __launch_bounds__(512, 2) trunk_fwd(Args a0) {
;     extern __shared__ __attribute__((aligned(16))) unsigned char lds_raw[];
;     LAS unsigned char* lds = (LAS unsigned char*)lds_raw;
;     const int G = gridDim.x, bx = blockIdx.x;
;     const int wv = __builtin_amdgcn_readfirstlane(threadIdx.x >> 6);
;     const int vcu = (G % 8 == 0) ? (bx % 8) * (G / 8) + bx / 8 : bx;
;     const int NGW = G * 8;
;     for (int u = opaque_tid(wv); u < (LDS_BYTES - 131072) / 4; u += 512) ((LAS unsigned*)(lds + 131072))[u] = 0u;
;     __syncthreads();
;     XcdBarrier bar = xcd_barrier_post((unsigned*)(a0.ws + WS_CTL) + 4096, (volatile LAS unsigned*)(lds + MISC_OFF) + 8, opaque_tid(wv));
.LBB0_8:
	s_or_b64 exec, exec, s[6:7]
	s_load_dwordx4 s[8:11], s[0:1], 0x88
	s_waitcnt lgkmcnt(0)
	s_cmp_ge_i32 s10, s11
	s_cbranch_scc1 .LBB0_882
	s_lshl_b32 s46, s33, 3
	s_cmpk_eq_i32 s33, 0x100
	s_cselect_b64 s[18:19], -1, 0
	s_cmpk_lg_i32 s33, 0x100
	s_cselect_b64 s[6:7], -1, 0
	s_cmp_lt_i32 s83, 32
	s_cselect_b64 s[8:9], -1, 0
	s_sub_i32 s3, s83, 33
	s_cmpk_eq_i32 s83, 0x41
	s_cselect_b64 s[10:11], -1, 0
	s_and_b64 s[12:13], s[10:11], exec
	s_cselect_b32 s17, 31, -1
	s_cmp_lt_u32 s3, 31
	s_cselect_b64 s[12:13], -1, 0
	s_and_b64 s[14:15], s[12:13], exec
	s_cselect_b32 s3, s3, s17
	s_cmpk_lt_i32 s83, 0x200
	s_load_dwordx16 s[48:63], s[0:1], 0x0
	s_load_dwordx16 s[64:79], s[0:1], 0x40
	v_writelane_b32 v252, s3, 6
	s_cselect_b64 s[14:15], -1, 0
	v_writelane_b32 v252, s14, 7
	s_mul_i32 s17, s83, 0xffffff78
	s_lshl_b32 s24, s83, 3
	v_writelane_b32 v252, s15, 8
	s_sub_i32 s14, s33, s83
	s_add_i32 s15, s14, 0x1ff
	s_add_i32 s3, s14, 31
	s_addk_i32 s17, 0x2080
	s_add_i32 s89, s33, s2
	s_ashr_i32 s28, s33, 31
	s_waitcnt lgkmcnt(0)
	s_cmp_lg_u64 s[54:55], 0
	s_cselect_b64 s[94:95], -1, 0
	s_cmp_lg_u64 s[66:67], 0
	v_writelane_b32 v252, s17, 9
	s_cselect_b64 s[20:21], -1, 0
	v_writelane_b32 v252, s20, 10
	s_cmp_lg_u64 s[64:65], 0
	v_lshrrev_b32_e32 v3, 20, v0
	v_writelane_b32 v252, s21, 11
	s_cselect_b64 s[20:21], -1, 0
	v_writelane_b32 v252, s20, 12
	s_lshl_b32 s26, s33, 4
	v_lshrrev_b32_e32 v0, 10, v0
	v_writelane_b32 v252, s21, 13
	s_load_dwordx4 s[20:23], s[0:1], 0x88
	v_or_b32_e32 v0, v0, v3
	s_load_dwordx2 s[0:1], s[0:1], 0x80
	v_mov_b32_e32 v229, 0x358637bd
	v_mov_b32_e32 v243, 1
	s_waitcnt lgkmcnt(0)
	s_add_u32 s22, s20, 0x4200
	s_addc_u32 s23, s21, 0
	v_writelane_b32 v252, s22, 14
	v_bfrev_b32_e32 v232, 1
	v_mov_b32_e32 v16, 0xf149f2ca
	v_writelane_b32 v252, s23, 15
	s_add_u32 s22, s20, 0x4400
	s_addc_u32 s23, s21, 0
	v_writelane_b32 v252, s22, 16
	v_mov_b32_e32 v233, 0x2400
	s_movk_i32 s98, 0x1000
	v_writelane_b32 v252, s23, 17
	s_add_u32 s22, s20, 0x4500
	s_addc_u32 s23, s21, 0
	v_writelane_b32 v252, s22, 18
	s_movk_i32 s29, 0x2400
	s_mov_b32 s97, 0x7e07e07f
	v_writelane_b32 v252, s23, 19
	s_add_u32 s22, s20, 0x4600
	s_addc_u32 s23, s21, 0
	v_writelane_b32 v252, s22, 20
	s_mov_b32 s91, 0
	s_nop 0
	v_writelane_b32 v252, s23, 21
	s_add_u32 s22, s20, 0x4700
	s_addc_u32 s23, s21, 0
	v_writelane_b32 v252, s22, 22
	s_nop 1
	v_writelane_b32 v252, s23, 23
	s_add_u32 s22, s20, 0x4800
	s_addc_u32 s23, s21, 0
	v_writelane_b32 v252, s22, 24
	s_nop 1
	v_writelane_b32 v252, s23, 25
	s_add_u32 s22, s20, 0x4900
	s_addc_u32 s23, s21, 0
	v_writelane_b32 v252, s22, 26
	s_nop 1
	v_writelane_b32 v252, s23, 27
	s_add_u32 s22, s20, 0x4a00
	s_addc_u32 s23, s21, 0
	v_writelane_b32 v252, s22, 28
	s_nop 1
	v_writelane_b32 v252, s23, 29
	s_add_u32 s22, s20, 0x4b00
	s_addc_u32 s23, s21, 0
	v_writelane_b32 v252, s22, 30
	s_nop 1
	v_writelane_b32 v252, s23, 31
	s_add_u32 s22, s20, 0x4c00
	s_addc_u32 s23, s21, 0
	v_writelane_b32 v252, s22, 32
	s_nop 1
	v_writelane_b32 v252, s23, 33
	s_add_u32 s22, s20, 0x4d00
	s_addc_u32 s23, s21, 0
	v_writelane_b32 v252, s22, 34
	s_nop 1
	v_writelane_b32 v252, s23, 35
	s_add_u32 s22, s20, 0x4e00
	s_addc_u32 s23, s21, 0
	v_writelane_b32 v252, s22, 36
	s_nop 1
	v_writelane_b32 v252, s23, 37
	s_add_u32 s22, s20, 0x4f00
	s_addc_u32 s23, s21, 0
	v_writelane_b32 v252, s22, 38
	s_nop 1
	v_writelane_b32 v252, s23, 39
	s_add_u32 s22, s20, 0x5000
	s_addc_u32 s23, s21, 0
	v_writelane_b32 v252, s22, 40
	s_nop 1
	v_writelane_b32 v252, s23, 41
	s_add_u32 s22, s20, 0x5100
	s_addc_u32 s23, s21, 0
	v_writelane_b32 v252, s22, 42
	s_nop 1
	v_writelane_b32 v252, s23, 43
	s_add_u32 s22, s20, 0x5200
	s_addc_u32 s23, s21, 0
	v_writelane_b32 v252, s22, 44
	s_nop 1
	v_writelane_b32 v252, s23, 45
	s_add_u32 s22, s20, 0x5300
	s_addc_u32 s23, s21, 0
	v_writelane_b32 v252, s22, 46
	s_cmp_eq_u32 s16, 15
	s_nop 0
	v_writelane_b32 v252, s23, 47
	s_cselect_b64 s[22:23], -1, 0
	v_writelane_b32 v252, s22, 48
	s_cmp_eq_u32 s16, 14
	s_nop 0
	v_writelane_b32 v252, s23, 49
	s_cselect_b64 s[22:23], -1, 0
	v_writelane_b32 v252, s22, 50
	s_cmp_eq_u32 s16, 13
	s_nop 0
	v_writelane_b32 v252, s23, 51
	s_cselect_b64 s[22:23], -1, 0
	v_writelane_b32 v252, s22, 52
	s_cmp_eq_u32 s16, 12
	s_nop 0
	v_writelane_b32 v252, s23, 53
	s_cselect_b64 s[22:23], -1, 0
	v_writelane_b32 v252, s22, 54
	s_cmp_eq_u32 s16, 11
	s_nop 0
	v_writelane_b32 v252, s23, 55
	s_cselect_b64 s[22:23], -1, 0
	v_writelane_b32 v252, s22, 56
	s_cmp_eq_u32 s16, 10
	s_nop 0
	v_writelane_b32 v252, s23, 57
	s_cselect_b64 s[22:23], -1, 0
	v_writelane_b32 v252, s22, 58
	s_cmp_eq_u32 s16, 9
	s_nop 0
	v_writelane_b32 v252, s23, 59
	s_cselect_b64 s[22:23], -1, 0
	v_writelane_b32 v252, s22, 60
	s_cmp_eq_u32 s16, 8
	s_nop 0
	v_writelane_b32 v252, s23, 61
	s_cselect_b64 s[22:23], -1, 0
	v_writelane_b32 v252, s22, 62
	s_cmp_eq_u32 s16, 7
	s_nop 0
	v_writelane_b32 v252, s23, 63
	s_cselect_b64 s[22:23], -1, 0
	v_writelane_b32 v253, s22, 0
	s_cmp_eq_u32 s16, 6
	s_nop 0
	v_writelane_b32 v253, s23, 1
	s_cselect_b64 s[22:23], -1, 0
	v_writelane_b32 v253, s22, 2
	s_cmp_eq_u32 s16, 5
	s_nop 0
	v_writelane_b32 v253, s23, 3
	s_cselect_b64 s[22:23], -1, 0
	v_writelane_b32 v253, s22, 4
	s_cmp_eq_u32 s16, 4
	s_nop 0
	v_writelane_b32 v253, s23, 5
	s_cselect_b64 s[22:23], -1, 0
	v_writelane_b32 v253, s22, 6
	s_cmp_eq_u32 s16, 3
	s_nop 0
	v_writelane_b32 v253, s23, 7
	s_cselect_b64 s[22:23], -1, 0
	v_writelane_b32 v253, s22, 8
	s_cmp_eq_u32 s16, 2
	s_nop 0
	v_writelane_b32 v253, s23, 9
	s_cselect_b64 s[22:23], -1, 0
	v_writelane_b32 v253, s22, 10
	s_cmp_eq_u32 s16, 1
	s_nop 0
; #define LAS __attribute__((address_space(3)))
; __device__ __forceinline__ int opaque_tid(int wv) { int t = wv * 64 + (int)__builtin_amdgcn_mbcnt_hi(~0u, __builtin_amdgcn_mbcnt_lo(~0u, 0u)); asm volatile("" : "+v"(t)); return t; }
; __device__ __forceinline__ void phase_attn(const Args& a, int l, LAS unsigned char* lds, int vcu, int G, int wv) {
;     ...
;     const int sp0 = (G == 256) ? ((vcu >= 33 && vcu < 64) ? vcu - 33 : (vcu == 65 ? 31 : -1)) : (vcu < 32 ? vcu : -1);
;     const int nmain = (vcu < 512) ? 2 * ((512 - vcu + G - 1) / G) : 0, nspec = (G == 256) ? (sp0 >= 0 ? 1 : 0) : ((vcu < 32) ? (32 - vcu + G - 1) / G : 0);
; __global__ void __launch_bounds__(512, 2) trunk_fwd(Args a0) {
;     extern __shared__ __attribute__((aligned(16))) unsigned char lds_raw[];
;     LAS unsigned char* lds = (LAS unsigned char*)lds_raw;
;     const int G = gridDim.x, bx = blockIdx.x;
;     const int wv = __builtin_amdgcn_readfirstlane(threadIdx.x >> 6);
;     const int vcu = (G % 8 == 0) ? (bx % 8) * (G / 8) + bx / 8 : bx;
;     const int NGW = G * 8;
;     for (int u = opaque_tid(wv); u < (LDS_BYTES - 131072) / 4; u += 512) ((LAS unsigned*)(lds + 131072))[u] = 0u;
;     __syncthreads();
;     XcdBarrier bar = xcd_barrier_post((unsigned*)(a0.ws + WS_CTL) + 4096, (volatile LAS unsigned*)(lds + MISC_OFF) + 8, opaque_tid(wv));
	v_writelane_b32 v253, s23, 11
	s_cselect_b64 s[22:23], -1, 0
	v_writelane_b32 v253, s22, 12
	s_cmp_eq_u32 s16, 0
	s_nop 0
	v_writelane_b32 v253, s23, 13
	s_cselect_b64 s[22:23], -1, 0
	s_lshl_b32 s2, s16, 8
	s_add_u32 s2, s4, s2
	s_addc_u32 s4, s5, 0
	v_writelane_b32 v253, s22, 14
	s_add_u32 s16, s2, 0x1400
	s_addc_u32 s17, s4, 0
	v_writelane_b32 v253, s23, 15
	v_writelane_b32 v253, s16, 16
	s_nop 1
	v_writelane_b32 v253, s17, 17
	s_add_u32 s16, s2, 0x2400
	s_addc_u32 s17, s4, 0
	v_writelane_b32 v253, s16, 18
	s_add_u32 s4, s20, 0x7400
	s_addc_u32 s5, s21, 0
	v_writelane_b32 v253, s17, 19
	v_writelane_b32 v253, s4, 20
	s_movk_i32 s2, 0x3ff
	v_and_or_b32 v0, v0, s2, v1
	v_writelane_b32 v253, s5, 21
	s_add_u32 s4, s20, 0x7500
	s_addc_u32 s5, s21, 0
	s_abs_i32 s99, s33
	v_cvt_f32_u32_e32 v1, s99
	v_writelane_b32 v253, s4, 22
	s_sub_i32 s2, 0, s99
	v_rcp_iflag_f32_e32 v1, v1
	v_writelane_b32 v253, s5, 23
	s_or_b64 s[4:5], s[12:13], s[10:11]
	v_writelane_b32 v253, s18, 24
	v_mul_f32_e32 v1, 0x4f7ffffe, v1
	v_cvt_u32_f32_e32 v1, v1
	s_and_b64 s[4:5], s[18:19], s[4:5]
	v_writelane_b32 v253, s19, 25
	v_cndmask_b32_e64 v2, 0, 1, s[4:5]
	s_and_b64 s[4:5], s[6:7], s[8:9]
	v_writelane_b32 v253, s4, 26
	s_mov_b64 s[10:11], 0x80
	s_nop 0
	v_writelane_b32 v253, s5, 27
	v_readfirstlane_b32 s4, v1
	s_mul_i32 s2, s2, s4
	s_mul_hi_u32 s2, s4, s2
	s_add_i32 s8, s4, s2
	s_sub_i32 s2, 0xfffffe01, s14
	s_max_i32 s2, s15, s2
	s_mul_hi_u32 s4, s2, s8
	s_mul_i32 s5, s4, s99
	s_sub_i32 s2, s2, s5
	s_ashr_i32 s5, s15, 31
	s_xor_b32 s5, s5, s28
	s_add_i32 s6, s4, 1
	s_sub_i32 s7, s2, s99
	s_cmp_ge_u32 s2, s99
	s_cselect_b32 s4, s6, s4
	s_cselect_b32 s2, s7, s2
	s_add_i32 s6, s4, 1
	s_cmp_ge_u32 s2, s99
	s_cselect_b32 s2, s6, s4
	s_sub_i32 s4, 0xffffffe1, s14
	s_xor_b32 s2, s2, s5
	s_max_i32 s4, s3, s4
	s_sub_i32 s2, s2, s5
	s_mul_hi_u32 s5, s4, s8
	v_writelane_b32 v253, s8, 28
	s_mul_i32 s6, s5, s99
	s_lshl_b32 s2, s2, 1
	s_sub_i32 s4, s4, s6
	v_writelane_b32 v253, s2, 29
	s_ashr_i32 s2, s3, 31
	s_xor_b32 s2, s2, s28
	s_add_i32 s3, s5, 1
	s_sub_i32 s6, s4, s99
	s_cmp_ge_u32 s4, s99
	s_cselect_b32 s3, s3, s5
	s_cselect_b32 s4, s6, s4
	s_add_i32 s5, s3, 1
	s_cmp_ge_u32 s4, s99
	s_cselect_b32 s3, s5, s3
	s_xor_b32 s3, s3, s2
	s_sub_i32 s2, s3, s2
	v_writelane_b32 v253, s2, 30
	v_writelane_b32 v253, s0, 31
	v_mov_b32_e32 v1, 0
	s_nop 0
	v_writelane_b32 v253, s1, 32
	s_add_u32 s0, s20, 0x2209000
	v_writelane_b32 v253, s0, 33
	s_addc_u32 s0, s21, 0
	v_writelane_b32 v253, s0, 34
	s_add_u32 s0, s20, 0x62fdc00
	v_writelane_b32 v253, s0, 35
	s_addc_u32 s0, s21, 0
	v_writelane_b32 v253, s0, 36
	s_mul_i32 s0, s83, 0x88
	v_writelane_b32 v253, s0, 37
	s_or_b32 s0, s0, 1
	v_writelane_b32 v253, s0, 38
	s_add_u32 s0, s64, 56
	v_writelane_b32 v253, s0, 39
	v_writelane_b32 v253, s64, 40
	s_addc_u32 s0, s65, 0
	s_nop 0
	v_writelane_b32 v253, s65, 41
	v_writelane_b32 v253, s66, 42
	v_writelane_b32 v253, s67, 43
	v_writelane_b32 v253, s68, 44
	v_writelane_b32 v253, s69, 45
	v_writelane_b32 v253, s70, 46
	v_writelane_b32 v253, s71, 47
	v_writelane_b32 v253, s72, 48
	v_writelane_b32 v253, s73, 49
	v_writelane_b32 v253, s74, 50
	v_writelane_b32 v253, s75, 51
	v_writelane_b32 v253, s76, 52
	v_writelane_b32 v253, s77, 53
	v_writelane_b32 v253, s78, 54
	v_writelane_b32 v253, s79, 55
	v_writelane_b32 v253, s0, 56
	s_add_u32 s0, s56, 0x800
	s_addc_u32 s1, s57, 0
	v_writelane_b32 v253, s0, 57
	s_nop 1
	v_writelane_b32 v253, s1, 58
	s_add_u32 s0, s54, 56
	s_addc_u32 s1, s55, 0
	v_writelane_b32 v253, s0, 59
	s_add_u32 s25, s56, 8
	s_nop 0
	v_writelane_b32 v253, s1, 60
	v_writelane_b32 v253, s48, 61
	s_addc_u32 s0, s57, 0
	s_nop 0
	v_writelane_b32 v254, s51, 0
	v_writelane_b32 v254, s52, 1
	v_writelane_b32 v254, s53, 2
	v_writelane_b32 v254, s54, 3
	v_writelane_b32 v254, s55, 4
	v_writelane_b32 v254, s56, 5
	v_writelane_b32 v254, s57, 6
	v_writelane_b32 v254, s58, 7
	v_writelane_b32 v254, s59, 8
	v_writelane_b32 v254, s60, 9
	v_writelane_b32 v254, s61, 10
	v_writelane_b32 v254, s62, 11
	v_writelane_b32 v254, s63, 12
	v_writelane_b32 v254, s0, 13
	s_add_u32 s0, s20, 0x1300000
	v_writelane_b32 v254, s0, 14
	s_addc_u32 s0, s21, 0
	v_writelane_b32 v254, s0, 15
	v_readfirstlane_b32 s0, v2
	s_ashr_i32 s27, s26, 31
	v_writelane_b32 v253, s49, 62
	v_writelane_b32 v254, s0, 16
	v_writelane_b32 v254, s24, 17
	s_ashr_i32 s0, s24, 31
	v_writelane_b32 v254, s0, 18
	s_lshl_b64 s[0:1], s[26:27], 7
	v_writelane_b32 v254, s0, 19
	v_writelane_b32 v253, s50, 63
	s_nop 0
	v_writelane_b32 v254, s1, 20
	s_add_u32 s0, s20, 0x1800000
	v_writelane_b32 v254, s0, 21
	s_addc_u32 s0, s21, 0
	v_writelane_b32 v254, s0, 22
	s_lshl_b64 s[0:1], s[26:27], 6
	v_writelane_b32 v254, s0, 23
	s_nop 1
	v_writelane_b32 v254, s1, 24
	s_add_u32 s0, s20, 0x2200400
	v_writelane_b32 v254, s0, 25
	s_addc_u32 s0, s21, 0
	v_writelane_b32 v254, s0, 26
	s_add_i32 s0, 0, 0x13800
	v_writelane_b32 v254, s0, 27
	s_add_i32 s0, 0, 0x20160
	v_writelane_b32 v254, s0, 28
	s_add_i32 s0, 0, 0x20164
	v_writelane_b32 v254, s0, 29
	v_cmp_eq_u32_e64 s[0:1], 0, v0
	s_mov_b64 s[20:21], s[26:27]
	s_movk_i32 s26, 0xdf80
	v_writelane_b32 v254, s0, 30
	s_movk_i32 s27, 0x6f
	s_nop 0
	v_writelane_b32 v254, s1, 31
	s_lshl_b64 s[0:1], s[20:21], 11
	v_writelane_b32 v254, s0, 32
	s_nop 1
	v_writelane_b32 v254, s1, 33
	v_writelane_b32 v254, s83, 34
	v_writelane_b32 v254, s46, 35
	s_mov_b32 s0, s20
	v_writelane_b32 v254, s0, 36
	s_nop 1
	v_writelane_b32 v254, s1, 37
	v_writelane_b32 v254, s89, 38
	v_writelane_b32 v254, s99, 39
	v_writelane_b32 v254, s25, 40
	s_mov_b32 s1, 0
	s_nop 1
	v_writelane_b32 v255, s1, 62
	s_branch .LBB0_14

; __global__ void __launch_bounds__(512, 2) trunk_fwd(Args a0) {
;     ...
;     for (int ph = a0.ph_lo; ph < a0.ph_hi; ++ph) {
;         Args a = a0; { size_t off = 0; asm volatile("" : "+s"(off)); a.ws = a0.ws + off; }
;         unsigned char* ws = a.ws;
;         if (ph == 0) phase_init(a, lds, vcu, NGW, wv);
;         else {
;             const int l = (ph - 1) / 5, sp = (ph - 1) % 5;
;             if (sp == 1) phase_pool(a, l, vcu, NGW, wv);
;             else if (sp == 2) phase_attn(a, l, lds, vcu, G, wv);
.LBB0_14:
	s_mov_b64 s[92:93], 0
	v_readlane_b32 s0, v252, 2
	v_readlane_b32 s1, v252, 3
	s_add_u32 s0, s0, s92
	v_readlane_b32 s2, v252, 4
	s_addc_u32 s1, s1, s93
	v_writelane_b32 v254, s0, 41
	s_cmp_lg_u32 s2, 0
	v_readlane_b32 s3, v252, 5
	v_writelane_b32 v254, s1, 42
	s_cselect_b64 s[0:1], -1, 0
	v_writelane_b32 v254, s0, 43
	s_and_b64 vcc, exec, s[0:1]
	s_nop 0
	v_writelane_b32 v254, s1, 44
	s_mov_b64 s[0:1], -1
	s_cbranch_vccz .LBB0_736
	v_readlane_b32 s0, v252, 2
	v_readlane_b32 s2, v252, 4
	v_readlane_b32 s1, v252, 3
	s_add_i32 s0, s2, -1
	s_mul_hi_i32 s1, s0, 0x66666667
	s_lshr_b32 s2, s1, 31
	s_ashr_i32 s1, s1, 1
	s_add_i32 s4, s1, s2
	v_readlane_b32 s3, v252, 5
	s_mul_i32 s1, s4, 5
	s_mov_b32 s2, s4
	s_sub_i32 s21, s0, s1
	v_writelane_b32 v254, s2, 45
	s_cmp_eq_u32 s21, 1
	s_cselect_b64 s[22:23], -1, 0
	v_writelane_b32 v254, s3, 46
	v_writelane_b32 v254, s21, 47
	v_writelane_b32 v254, s22, 48
	s_cmp_lg_u32 s21, 1
	s_mov_b64 s[0:1], -1
	s_mul_hi_i32 s8, s4, 0x180
	s_mul_i32 s9, s4, 0x180
	v_writelane_b32 v254, s23, 49
	s_cbranch_scc0 .LBB0_215
	s_cmp_lg_u32 s21, 2
	s_cbranch_scc1 .Lpf_16_done
	v_readlane_b32 s2, v254, 34
	v_readlane_b32 s3, v255, 62
	s_nop 3
	s_bfe_u32 s2, s2, 0x10004
	s_cmp_eq_u32 s2, 0
	s_cbranch_scc1 .Lpf_16_done
	s_cmp_lg_u32 s3, 0
	s_cbranch_scc1 .Lpf_16_done
	s_mov_b32 s3, 1
	s_nop 0
	v_writelane_b32 v255, s3, 62
	s_branch .LBB0_214
.Lpf_16_done:
	s_cmp_lg_u32 s21, 2
	s_cbranch_scc1 .LBB0_214
	v_readlane_b32 s36, v253, 40
	v_readlane_b32 s44, v253, 48
	v_readlane_b32 s45, v253, 49
	s_add_u32 s2, s44, s9
	v_readlane_b32 s46, v253, 50
	s_addc_u32 s3, s45, s8
	v_readlane_b32 s47, v253, 51
	s_add_u32 s4, s46, s9
	s_addc_u32 s5, s47, s8
	s_mov_b64 s[0:1], 0
	s_waitcnt vmcnt(0)
	v_mov_b32_e32 v2, 0
	v_mov_b32_e32 v0, 0
	v_readlane_b32 s37, v253, 41
	v_readlane_b32 s38, v253, 42
	v_readlane_b32 s39, v253, 43
	v_readlane_b32 s40, v253, 44
	v_readlane_b32 s41, v253, 45
	v_readlane_b32 s42, v253, 46
	v_readlane_b32 s43, v253, 47
	v_readlane_b32 s48, v253, 52
	v_readlane_b32 s49, v253, 53
	v_readlane_b32 s50, v253, 54
	v_readlane_b32 s51, v253, 55

; __global__ void __launch_bounds__(512, 2) trunk_fwd(Args a0) {
;     ...
;             for (int j = 0; j < 3; ++j) {
;                 pg8::Gemm g{nullptr, 0, nullptr, 0, MP, 0, 0, 0};
;                 EpiAll E{K_IN, ws, a.out, a.kn_gain + (size_t)l * 96, (l == 0) ? a.x : nullptr, a.meta, (l == DEPTH - 1) ? 1 : 0};
;                 const bf16_t* PROJ = (const bf16_t*)(ws + WS_PROJ); const unsigned char* wb = ws + WS_W;
;                 if (sp == 0 && j == 0)      { g.A = (const bf16_t*)(ws + WS_H); g.lda = 1024; g.Bt = (const bf16_t*)(wb + W_IN); g.ldb = 1024; g.N = NIN_PAD; g.K = 1024; E.kind = K_IN; }
;                 else if (sp == 1 && j == 0) { g.A = PROJ + C_CQ; g.lda = PW; g.Bt = (const bf16_t*)(wb + W_Q); g.ldb = 768; g.N = 768; g.K = 768; E.kind = K_Q; }
;                 else if (sp == 1 && j == 1) { g.A = PROJ + C_CKV; g.lda = PW; g.Bt = (const bf16_t*)(wb + W_KV); g.ldb = 256; g.N = 512; g.K = 256; E.kind = K_KV; }
;                 else if (sp == 1 && j == 2) { g.A = (const bf16_t*)(wb + W_KV) + 512 * 256; g.lda = 256; g.Bt = PROJ + C_CKV; g.ldb = PW; g.M = 512; g.N = MP; g.K = 256; E.kind = K_VT; }
;                 else if (sp == 2 && j == 0) { g.A = PROJ + C_P1Y; g.lda = PW; g.Bt = (const bf16_t*)(wb + W_PU); g.ldb = 512; g.N = 1024; g.K = 512; E.kind = K_POOLUP; }
;                 else if (sp == 3 && j == 0) { g.A = PROJ + C_OZ; g.lda = PW; g.Bt = (const bf16_t*)(wb + W_MU); g.ldb = 512; g.N = 1024; g.K = 512; E.kind = K_MLAUP; }
;                 else if (sp == 4 && j == 0) { g.A = (const bf16_t*)(ws + WS_QRAW)  ; g.lda = 1024; g.Bt = (const bf16_t*)(wb + W_O) + (size_t)(l & 1) * 1024 * 1024; g.ldb = 1024; g.N = 1024; g.K = 1024; E.kind = K_OUT; }
;                 else break;
;                 const int rot = (E.kind == K_KV) ? 134 : (E.kind == K_VT) ? 138 : 0;
;                 pg8::StaticOrder S; S.init(g.M, g.N, G, (bx + G - rot % G) % G); pg8::gemm_phase(lds, g, S, E, wv);
.LBB0_235:
	v_readlane_b32 s0, v255, 62
	s_nop 3
	s_cmp_eq_u32 s0, 2
	s_cbranch_scc0 .Lpf_235_go
	s_mov_b64 s[4:5], -1
	s_branch .LBB0_234

; __device__ __forceinline__ int opaque_tid(int wv) { int t = wv * 64 + (int)__builtin_amdgcn_mbcnt_hi(~0u, __builtin_amdgcn_mbcnt_lo(~0u, 0u)); asm volatile("" : "+v"(t)); return t; }
; __global__ void __launch_bounds__(512, 2) trunk_fwd(Args a0) {
;     ...
;         if (ph + 1 < a0.ph_hi) { if (ph == 0) { __syncthreads(); cg::this_grid().sync(); } else xcd_barrier(bar, opaque_tid(wv)); }
.LBB0_817:
	v_readlane_b32 s2, v255, 62
	s_nop 3
	s_cmp_eq_u32 s2, 1
	s_cbranch_scc0 .Lpf_817_a
	s_mov_b32 s2, 2
	s_nop 0
	v_writelane_b32 v255, s2, 62
	v_readlane_b32 s25, v254, 40
	s_branch .LBB0_12
.Lpf_817_a:
	s_cmp_eq_u32 s2, 2
	s_cbranch_scc0 .Lpf_817_b
	s_mov_b32 s2, 0
	s_nop 0
	v_writelane_b32 v255, s2, 62
